# P5: the first row block's rstd values computed in the phase prologue (beside the wait for the first K-tiles) instead of in the first tile's epilogue
# baseline (speedup 1.0000x reference)
;     __device__ __forceinline__ void operator()(const f32x4 (&acc)[2][2][4][2], const Unit& u, int wr, int wc, int fr, int fq) const {
;     ...
;         f32x4 sq[2][4];
; #pragma unroll
;         for (int ai = 0; ai < 2; ++ai)
; #pragma unroll
;             for (int m = 0; m < 4; ++m) sq[ai][m] = *(const f32x4*)(SSQ + (size_t)(row0 + ai * HALF + m * 16) * 16 + 4 * fq);
; #pragma unroll
;         for (int ai = 0; ai < 2; ++ai)
; #pragma unroll
;             for (int m = 0; m < 4; ++m) {
;                 const int row = row0 + ai * HALF + m * 16;
;                 float ss = (sq[ai][m][0] + sq[ai][m][1]) + (sq[ai][m][2] + sq[ai][m][3]);
;                 ss += __shfl_xor(ss, 16); ss += __shfl_xor(ss, 32);
;                 const float rstd = __builtin_amdgcn_rsqf(ss * (1.0f / 1024.0f) + 1e-6f);
.LBB0_963:
	s_add_u32 s8, s72, 0x4b00000
	s_addc_u32 s9, s73, 0
	s_lshl_b32 s10, s10, 5
	s_and_b32 s15, s10, 0x60
	s_mov_b64 s[10:11], 0x80
	s_add_i32 m0, s39, 0x18000
	v_lshl_add_u64 v[6:7], v[6:7], 0, s[10:11]
	s_lshl_b32 s14, s4, 13
	s_lshl_b32 s16, s15, 7
	s_waitcnt vmcnt(2)
	s_barrier
	global_load_lds_dwordx4 v[6:7], off
	v_lshl_add_u64 v[4:5], v[4:5], 0, s[10:11]
	s_add_i32 m0, s39, 0x1a000
	s_add_i32 s43, s39, 0x8000
	s_add_i32 s44, s39, 0xa000
	global_load_lds_dwordx4 v[4:5], off
	v_lshl_add_u64 v[0:1], v[0:1], 0, s[10:11]
	s_mov_b32 m0, s43
	s_add_u32 s12, s26, 0x40080
	global_load_lds_dwordx4 v[0:1], off
	v_lshl_add_u64 v[0:1], v[2:3], 0, s[10:11]
	s_mov_b32 m0, s44
	s_addc_u32 s13, s27, 0
	global_load_lds_dwordx4 v[0:1], off
	s_add_i32 m0, s39, 0x1c000
	v_lshl_add_u64 v[0:1], s[12:13], 0, v[156:157]
	global_load_lds_dwordx4 v[0:1], off
	v_lshl_add_u64 v[0:1], s[12:13], 0, v[152:153]
	s_add_i32 m0, s39, 0x1e000
	v_bfe_u32 v2, v10, 4, 2
	global_load_lds_dwordx4 v[0:1], off
	v_and_b32_e32 v1, 15, v10
	v_lshlrev_b32_e32 v0, 3, v2
	v_lshlrev_b32_e32 v160, 4, v2
	v_lshlrev_b32_e32 v2, 2, v10
	v_lshl_or_b32 v189, s4, 6, v1
	v_lshl_or_b32 v1, v1, 6, v160
	v_and_b32_e32 v2, 32, v2
	v_bitop3_b32 v4, v1, s14, v2 bitop3:0xde
	v_bitop3_b32 v190, v1, s16, v2 bitop3:0xde
	v_lshlrev_b32_e32 v1, 14, v13
	s_sext_i32_i16 s23, s2
	s_cmpk_lt_u32 s3, 0x100
	v_lshl_add_u64 v[2:3], s[72:73], 0, v[160:161]
	s_mov_b64 s[2:3], 0x100000
	v_and_b32_e32 v1, 0xffff8000, v1
	v_lshl_add_u64 v[162:163], v[2:3], 0, s[2:3]
	v_lshl_add_u32 v1, v12, 11, v1
	v_and_b32_e32 v2, 1, v13
	v_lshl_or_b32 v1, v2, 6, v1
	v_lshl_add_u32 v164, v14, 1, v1
	v_lshlrev_b32_e32 v1, 14, v8
	v_and_b32_e32 v1, 0xffff8000, v1
	v_lshl_add_u32 v1, v9, 11, v1
	v_and_b32_e32 v2, 1, v8
	s_waitcnt vmcnt(6)
	v_lshl_or_b32 v1, v2, 6, v1
	s_cselect_b64 s[12:13], -1, 0
	v_lshl_add_u32 v166, v11, 1, v1
	s_add_i32 s47, 0, 0x10000
	s_add_i32 s48, 0, 0x14000
	v_mbcnt_lo_u32_b32 v1, -1, 0
	s_ashr_i32 s45, s84, 31
	s_mov_b32 s46, s84
	v_mov_b32_e32 v165, v161
	v_mov_b32_e32 v167, v161
	v_mov_b64_e32 v[168:169], 0x580
	v_mov_b64_e32 v[170:171], 0x57f
	v_add_u32_e32 v191, s47, v190
	v_add_u32_e32 v192, s48, v190
	v_add_u32_e32 v193, 0, v4
	v_mbcnt_hi_u32_b32 v194, -1, v1
	v_mov_b32_e32 v195, 0x358637bd
	s_movk_i32 s49, 0x1600
	s_lshl_b32 s4, s15, 1
	v_lshlrev_b32_e32 v160, 1, v0
	s_mov_b32 s100, s22
	v_lshl_add_u32 v244, s22, 8, v189
	v_xor_b32_e32 v252, 16, v194
	v_xor_b32_e32 v253, 32, v194
	v_lshlrev_b32_e32 v252, 2, v252
	v_lshlrev_b32_e32 v253, 2, v253
	v_add_u32_e32 v250, 0, v244
	v_mov_b32_e32 v251, 0
	v_lshlrev_b64 v[250:251], 6, v[250:251]
	v_lshl_add_u64 v[250:251], v[162:163], 0, v[250:251]
	global_load_dwordx4 v[220:223], v[250:251], off
	v_add_u32_e32 v250, 16, v244
	v_mov_b32_e32 v251, 0
	v_lshlrev_b64 v[250:251], 6, v[250:251]
	v_lshl_add_u64 v[250:251], v[162:163], 0, v[250:251]
	global_load_dwordx4 v[224:227], v[250:251], off
	v_add_u32_e32 v250, 32, v244
	v_mov_b32_e32 v251, 0
	v_lshlrev_b64 v[250:251], 6, v[250:251]
	v_lshl_add_u64 v[250:251], v[162:163], 0, v[250:251]
	global_load_dwordx4 v[228:231], v[250:251], off
	v_add_u32_e32 v250, 48, v244
	v_mov_b32_e32 v251, 0
	v_lshlrev_b64 v[250:251], 6, v[250:251]
	v_lshl_add_u64 v[250:251], v[162:163], 0, v[250:251]
	global_load_dwordx4 v[232:235], v[250:251], off
	s_waitcnt vmcnt(3)
	v_add_f32_e32 v220, v220, v221
	v_add_f32_e32 v222, v222, v223
	v_add_f32_e32 v220, v220, v222
	ds_bpermute_b32 v221, v252, v220
	s_waitcnt vmcnt(2)
	v_add_f32_e32 v224, v224, v225
	v_add_f32_e32 v226, v226, v227
	v_add_f32_e32 v224, v224, v226
	ds_bpermute_b32 v225, v252, v224
	s_waitcnt vmcnt(1)
	v_add_f32_e32 v228, v228, v229
	v_add_f32_e32 v230, v230, v231
	v_add_f32_e32 v228, v228, v230
	ds_bpermute_b32 v229, v252, v228
	s_waitcnt vmcnt(0)
	v_add_f32_e32 v232, v232, v233
	v_add_f32_e32 v234, v234, v235
	v_add_f32_e32 v232, v232, v234
	ds_bpermute_b32 v233, v252, v232
	s_waitcnt lgkmcnt(3)
	v_add_f32_e32 v220, v220, v221
	s_waitcnt lgkmcnt(2)
	v_add_f32_e32 v224, v224, v225
	s_waitcnt lgkmcnt(1)
	v_add_f32_e32 v228, v228, v229
	s_waitcnt lgkmcnt(0)
	v_add_f32_e32 v232, v232, v233
	ds_bpermute_b32 v221, v253, v220
	ds_bpermute_b32 v225, v253, v224
	ds_bpermute_b32 v229, v253, v228
	ds_bpermute_b32 v233, v253, v232
	s_waitcnt lgkmcnt(3)
	v_add_f32_e32 v220, v220, v221
	v_fmamk_f32 v220, v220, 0x3a800000, v195
	v_rsq_f32_e32 v236, v220
	s_waitcnt lgkmcnt(2)
	v_add_f32_e32 v224, v224, v225
	v_fmamk_f32 v224, v224, 0x3a800000, v195
	v_rsq_f32_e32 v237, v224
	s_waitcnt lgkmcnt(1)
	v_add_f32_e32 v228, v228, v229
	v_fmamk_f32 v228, v228, 0x3a800000, v195
	v_rsq_f32_e32 v238, v228
	s_waitcnt lgkmcnt(0)
	v_add_f32_e32 v232, v232, v233
	v_fmamk_f32 v232, v232, 0x3a800000, v195
	v_rsq_f32_e32 v239, v232
	v_add_u32_e32 v250, 128, v244
	v_mov_b32_e32 v251, 0
	v_lshlrev_b64 v[250:251], 6, v[250:251]
	v_lshl_add_u64 v[250:251], v[162:163], 0, v[250:251]
	global_load_dwordx4 v[220:223], v[250:251], off
	v_add_u32_e32 v250, 144, v244
	v_mov_b32_e32 v251, 0
	v_lshlrev_b64 v[250:251], 6, v[250:251]
	v_lshl_add_u64 v[250:251], v[162:163], 0, v[250:251]
	global_load_dwordx4 v[224:227], v[250:251], off
	v_add_u32_e32 v250, 160, v244
	v_mov_b32_e32 v251, 0
	v_lshlrev_b64 v[250:251], 6, v[250:251]
	v_lshl_add_u64 v[250:251], v[162:163], 0, v[250:251]
	global_load_dwordx4 v[228:231], v[250:251], off
	v_add_u32_e32 v250, 176, v244
	v_mov_b32_e32 v251, 0
	v_lshlrev_b64 v[250:251], 6, v[250:251]
	v_lshl_add_u64 v[250:251], v[162:163], 0, v[250:251]
	global_load_dwordx4 v[232:235], v[250:251], off
	s_waitcnt vmcnt(3)
	v_add_f32_e32 v220, v220, v221
	v_add_f32_e32 v222, v222, v223
	v_add_f32_e32 v220, v220, v222
	ds_bpermute_b32 v221, v252, v220
	s_waitcnt vmcnt(2)
	v_add_f32_e32 v224, v224, v225
	v_add_f32_e32 v226, v226, v227
	v_add_f32_e32 v224, v224, v226
	ds_bpermute_b32 v225, v252, v224
	s_waitcnt vmcnt(1)
	v_add_f32_e32 v228, v228, v229
	v_add_f32_e32 v230, v230, v231
	v_add_f32_e32 v228, v228, v230
	ds_bpermute_b32 v229, v252, v228
	s_waitcnt vmcnt(0)
	v_add_f32_e32 v232, v232, v233
	v_add_f32_e32 v234, v234, v235
	v_add_f32_e32 v232, v232, v234
	ds_bpermute_b32 v233, v252, v232
	s_waitcnt lgkmcnt(3)
	v_add_f32_e32 v220, v220, v221
	s_waitcnt lgkmcnt(2)
	v_add_f32_e32 v224, v224, v225
	s_waitcnt lgkmcnt(1)
	v_add_f32_e32 v228, v228, v229
	s_waitcnt lgkmcnt(0)
	v_add_f32_e32 v232, v232, v233
	ds_bpermute_b32 v221, v253, v220
	ds_bpermute_b32 v225, v253, v224
	ds_bpermute_b32 v229, v253, v228
	ds_bpermute_b32 v233, v253, v232
	s_waitcnt lgkmcnt(3)
	v_add_f32_e32 v220, v220, v221
	v_fmamk_f32 v220, v220, 0x3a800000, v195
	v_rsq_f32_e32 v240, v220
	s_waitcnt lgkmcnt(2)
	v_add_f32_e32 v224, v224, v225
	v_fmamk_f32 v224, v224, 0x3a800000, v195
	v_rsq_f32_e32 v241, v224
	s_waitcnt lgkmcnt(1)
	v_add_f32_e32 v228, v228, v229
	v_fmamk_f32 v228, v228, 0x3a800000, v195
	v_rsq_f32_e32 v242, v228
	s_waitcnt lgkmcnt(0)
	v_add_f32_e32 v232, v232, v233
	v_fmamk_f32 v232, v232, 0x3a800000, v195
	v_rsq_f32_e32 v243, v232
	s_mov_b32 s50, s5
	s_barrier
	s_branch .LBB0_966
